# attention prompt tile start: gate-logit and compressed-block K/V loads requested together with q (one round trip instead of four)
# baseline (speedup 1.0000x reference)
.LBB0_1398:
	v_mov_b32_e32 v1, v0
	s_nop 0
	v_readfirstlane_b32 s7, v1
	v_cmp_gt_i32_e32 vcc, 4, v1
	s_and_saveexec_b64 s[0:1], vcc
	v_lshl_add_u32 v2, v1, 2, 0
	v_add_u32_e32 v2, 0x12400, v2
	ds_write_b32 v2, v165
	s_or_b64 exec, exec, s[0:1]
	s_waitcnt vmcnt(3)
	v_bfe_u32 v67, v1, 3, 1
	v_lshl_or_b32 v22, s76, 2, v67
	v_add_u32_e32 v12, 1, v22
	v_cvt_f32_u32_e32 v12, v12
	s_lshr_b32 s0, s10, 31
	v_add_u32_e32 v20, 3, v22
	s_add_i32 s0, s10, s0
	v_cvt_f32_u32_e32 v20, v20
	s_lshr_b32 s1, s0, 1
	s_and_b32 s0, s0, -2
	v_mul_f32_e32 v12, 0xc1000000, v12
	s_sub_i32 s81, 0, s1
	s_sub_i32 s0, s10, s0
	s_lshl_b32 s1, s1, 6
	v_mul_f32_e32 v13, 0x3d800000, v12
	s_sub_i32 s6, 0x1fc0, s1
	s_ashr_i32 s1, s0, 31
	v_cmp_gt_f32_e32 vcc, s54, v13
	s_lshl_b64 s[78:79], s[0:1], 13
	v_mul_f32_e32 v20, 0xc1000000, v20
	v_cndmask_b32_e32 v13, 0, v169, vcc
	s_add_u32 s2, s78, s6
	v_fmac_f32_e32 v13, 0x3d800000, v12
	v_mul_f32_e32 v21, 0x3d800000, v20
	s_addc_u32 s3, s79, 0
	s_ashr_i32 s7, s7, 6
	v_exp_f32_e32 v12, v13
	v_cndmask_b32_e32 v13, 0, v172, vcc
	v_cmp_gt_f32_e32 vcc, s54, v21
	v_and_b32_e32 v108, 7, v1
	s_lshl_b32 s11, s7, 3
	v_cndmask_b32_e32 v21, 0, v169, vcc
	v_or_b32_e32 v2, s11, v108
	v_fmac_f32_e32 v21, 0x3d800000, v20
	v_ashrrev_i32_e32 v3, 31, v2
	v_exp_f32_e32 v20, v21
	v_lshl_add_u64 v[18:19], s[2:3], 0, v[2:3]
	v_readlane_b32 s8, v240, 23
	v_add_u32_e32 v158, s6, v2
	v_lshlrev_b64 v[2:3], 11, v[18:19]
	v_readlane_b32 s9, v240, 24
	v_cndmask_b32_e32 v21, 0, v172, vcc
	v_and_b32_e32 v150, 48, v1
	v_lshl_add_u64 v[2:3], s[8:9], 0, v[2:3]
	v_readlane_b32 s8, v240, 10
	v_mov_b32_e32 v151, v165
	v_ldexp_f32 v20, v20, v21
	v_readlane_b32 s9, v240, 11
	v_lshl_add_u64 v[10:11], v[2:3], 0, v[150:151]
	v_lshlrev_b32_e32 v164, 6, v22
	v_mul_f32_e32 v148, 0x3fb8aa3b, v20
	v_mov_b64_e32 v[20:21], s[8:9]
	v_lshl_add_u64 v[2:3], v[164:165], 1, v[10:11]
	v_or_b32_e32 v164, 0x80, v164
	v_mad_u64_u32 v[20:21], s[8:9], v18, s55, v[20:21]
	v_mul_u32_u24_e32 v18, 3, v22
	v_lshl_add_u64 v[10:11], v[164:165], 1, v[10:11]
	v_mad_i32_i24 v21, v19, s55, v21
	v_lshlrev_b32_e32 v164, 2, v18
	v_readlane_b32 s12, v241, 0
	v_ldexp_f32 v12, v12, v13
	v_lshl_add_u64 v[26:27], v[20:21], 0, v[164:165]
	v_readlane_b32 s24, v241, 12
	v_readlane_b32 s25, v241, 13
	global_load_dwordx4 v[6:9], v[2:3], off
	s_nop 0
	global_load_dwordx4 v[2:5], v[2:3], off offset:64
	v_mul_f32_e32 v146, 0x3fb8aa3b, v12
	global_load_dwordx4 v[14:17], v[10:11], off
	s_nop 0
	global_load_dwordx4 v[10:13], v[10:11], off offset:64
	s_waitcnt vmcnt(4)
	v_ashrrev_i32_e32 v62, 3, v1
	global_load_dwordx3 v[18:20], v[26:27], off
	global_load_dwordx3 v[22:24], v164, s[24:25]
	s_lshl_b64 s[0:1], s[0:1], 7
	v_ashrrev_i32_e32 v63, 31, v62
	v_lshlrev_b32_e32 v156, 3, v1
	v_and_b32_e32 v100, 56, v156
	global_load_dwordx3 v[52:54], v[26:27], off offset:24
	global_load_dwordx3 v[56:58], v164, s[24:25] offset:24
	v_lshl_add_u64 v[60:61], s[0:1], 0, v[62:63]
	v_lshlrev_b64 v[60:61], 11, v[60:61]
	v_lshl_add_u64 v[60:61], s[52:53], 0, v[60:61]
	s_lshl_b32 s98, s76, 9
	s_mov_b32 s99, s77
	v_lshl_add_u64 v[60:61], v[60:61], 0, s[98:99]
	v_lshlrev_b32_e32 v126, 2, v100
	v_mov_b32_e32 v127, 0
	v_lshl_add_u64 v[34:35], v[60:61], 0, v[126:127]
	global_load_dwordx4 v[36:39], v[34:35], off offset:16
	global_load_dwordx4 v[40:43], v[34:35], off
	global_load_dwordx4 v[44:47], v[34:35], off offset:272
	global_load_dwordx4 v[48:51], v[34:35], off offset:256
	s_mov_b64 s[98:99], 0x20000
	v_lshl_add_u64 v[60:61], v[34:35], 0, s[98:99]
	global_load_dwordx4 v[110:113], v[60:61], off
	global_load_dwordx4 v[114:117], v[60:61], off offset:16
	global_load_dwordx4 v[118:121], v[60:61], off offset:272
	global_load_dwordx4 v[122:125], v[60:61], off offset:256
	v_mul_lo_u32 v97, v62, s56
	v_lshlrev_b32_e32 v151, 4, v1
	v_and_b32_e32 v96, 0x70, v151
	v_and_b32_e32 v65, 15, v1
	v_add_u32_e32 v98, 0, v150
	v_mad_u32_u24 v83, v65, s56, v98
	v_bfe_u32 v82, v1, 4, 2
	s_mulk_i32 s7, 0x1080
	v_readlane_b32 s21, v241, 9
	v_readlane_b32 s26, v241, 14
	s_mov_b64 s[82:83], s[52:53]
	s_add_i32 s7, s7, 0
	v_lshlrev_b32_e32 v99, 3, v82
	v_readlane_b32 s13, v241, 1
	v_readlane_b32 s14, v241, 2
	v_readlane_b32 s15, v241, 3
	v_readlane_b32 s16, v241, 4
	v_readlane_b32 s17, v241, 5
	v_readlane_b32 s18, v241, 6
	v_readlane_b32 s19, v241, 7
	v_readlane_b32 s20, v241, 8
	v_readlane_b32 s22, v241, 10
	v_readlane_b32 s23, v241, 11
	v_readlane_b32 s27, v241, 15
	s_waitcnt vmcnt(10)
	v_add_f32_e32 v21, v18, v22
	v_add_f32_e32 v25, v19, v23
	v_add_f32_e32 v28, v20, v24
	v_lshlrev_b32_e32 v164, 2, v100
	s_waitcnt vmcnt(8)
	v_add_f32_e32 v22, v52, v56
	v_mul_f32_e32 v18, 0xbfb8aa3b, v21
	v_mul_f32_e32 v21, 0xbfb8aa3b, v22
	v_exp_f32_e32 v18, v18
	v_exp_f32_e32 v21, v21
	v_add_f32_e32 v19, v53, v57
	v_add_f32_e32 v23, v54, v58
	v_add_f32_e32 v18, 1.0, v18
	v_add_f32_e32 v21, 1.0, v21
	v_rcp_f32_e32 v66, v18
	v_mul_f32_e32 v18, 0xbfb8aa3b, v25
	v_mul_f32_e32 v20, 0xbfb8aa3b, v28
	v_rcp_f32_e32 v64, v21
	v_mul_f32_e32 v19, 0xbfb8aa3b, v19
	v_mul_f32_e32 v21, 0xbfb8aa3b, v23
	v_exp_f32_e32 v18, v18
	v_exp_f32_e32 v20, v20
	v_exp_f32_e32 v19, v19
	v_exp_f32_e32 v21, v21
	v_add_f32_e32 v18, 1.0, v18
	v_add_f32_e32 v20, 1.0, v20
	v_add_f32_e32 v19, 1.0, v19
	v_add_f32_e32 v21, 1.0, v21
	v_rcp_f32_e32 v18, v18
	v_rcp_f32_e32 v20, v20
	v_rcp_f32_e32 v19, v19
	v_rcp_f32_e32 v21, v21
	v_lshl_add_u32 v22, v1, 5, 0
	v_add_u32_e32 v157, 0x12440, v22
	ds_write_b128 v157, v[18:21]
	s_lshl_b32 s0, s76, 9
	s_mov_b32 s1, s77
	s_mov_b32 s8, s0
	s_mov_b64 s[0:1], 0x20000
	v_writelane_b32 v240, s8, 48
	s_waitcnt vmcnt(6)
	v_cvt_pk_bf16_f32 v22, v40, v41
	v_cvt_pk_bf16_f32 v23, v42, v43
	v_cvt_pk_bf16_f32 v25, v38, v39
	s_waitcnt vmcnt(5)
	v_cvt_pk_bf16_f32 v20, v44, v45
	v_add_u32_e32 v26, 0, v97
	v_cvt_pk_bf16_f32 v24, v36, v37
	s_waitcnt vmcnt(4)
	v_cvt_pk_bf16_f32 v18, v48, v49
	v_add_u32_e32 v159, v26, v96
	s_mov_b32 s0, 0x20000
	v_cvt_pk_bf16_f32 v19, v50, v51
	v_cvt_pk_bf16_f32 v21, v46, v47
	ds_write_b128 v159, v[22:25]
	ds_write_b128 v159, v[18:21] offset:10240
	v_writelane_b32 v240, s9, 49
	s_nop 0
	s_nop 0
	s_nop 0
	s_waitcnt vmcnt(3)
	v_cvt_pk_bf16_f32 v22, v110, v111
	v_cvt_pk_bf16_f32 v23, v112, v113
	s_waitcnt vmcnt(2)
	v_cvt_pk_bf16_f32 v24, v114, v115
	v_cvt_pk_bf16_f32 v25, v116, v117
	s_waitcnt vmcnt(0)
	v_cvt_pk_bf16_f32 v26, v122, v123
	v_cvt_pk_bf16_f32 v27, v124, v125
	v_cvt_pk_bf16_f32 v28, v118, v119
	v_cvt_pk_bf16_f32 v29, v120, v121
	v_add_u32_e32 v18, 1, v158
	ds_write_b128 v159, v[22:25] offset:20480
	ds_write_b128 v159, v[26:29] offset:30720
	s_waitcnt lgkmcnt(0)
	s_barrier
	v_ashrrev_i32_e32 v130, 6, v18
	ds_read_b128 v[18:21], v83
	ds_read_b128 v[22:25], v83 offset:2560
	ds_read_b128 v[26:29], v83 offset:5120
	ds_read_b128 v[30:33], v83 offset:7680
	ds_read_b128 v[34:37], v83 offset:64
	ds_read_b128 v[38:41], v83 offset:2624
	ds_read_b128 v[42:45], v83 offset:5184
	ds_read_b128 v[50:53], v83 offset:7744
	s_setprio 1
	s_waitcnt lgkmcnt(7)
	v_mfma_f32_16x16x32_bf16 v[46:49], v[18:21], v[6:9], 0
	v_mfma_f32_16x16x32_bf16 v[54:57], v[18:21], v[14:17], 0
	s_waitcnt lgkmcnt(6)
	v_mfma_f32_16x16x32_bf16 v[58:61], v[22:25], v[6:9], 0
	v_mfma_f32_16x16x32_bf16 v[68:71], v[22:25], v[14:17], 0
	s_waitcnt lgkmcnt(5)
	v_mfma_f32_16x16x32_bf16 v[72:75], v[26:29], v[6:9], 0
	s_waitcnt lgkmcnt(4)
	v_mfma_f32_16x16x32_bf16 v[76:79], v[30:33], v[6:9], 0
	v_mfma_f32_16x16x32_bf16 v[84:87], v[30:33], v[14:17], 0
	v_mfma_f32_16x16x32_bf16 v[26:29], v[26:29], v[14:17], 0
	s_waitcnt lgkmcnt(3)
	v_mfma_f32_16x16x32_bf16 v[18:21], v[34:37], v[2:5], v[46:49]
	v_mfma_f32_16x16x32_bf16 v[46:49], v[34:37], v[10:13], v[54:57]
	s_waitcnt lgkmcnt(2)
	v_mfma_f32_16x16x32_bf16 v[22:25], v[38:41], v[2:5], v[58:61]
	v_mfma_f32_16x16x32_bf16 v[58:61], v[38:41], v[10:13], v[68:71]
	s_waitcnt lgkmcnt(1)
	v_mfma_f32_16x16x32_bf16 v[30:33], v[42:45], v[2:5], v[72:75]
	s_waitcnt lgkmcnt(0)
	v_mfma_f32_16x16x32_bf16 v[38:41], v[50:53], v[2:5], v[76:79]
	v_mfma_f32_16x16x32_bf16 v[74:77], v[50:53], v[10:13], v[84:87]
	v_mfma_f32_16x16x32_bf16 v[92:95], v[42:45], v[10:13], v[26:29]
	s_setprio 0
	s_nop 1
	ds_read_b128 v[26:29], v83 offset:20480
	ds_read_b128 v[34:37], v83 offset:20544
	ds_read_b128 v[42:45], v83 offset:23040
	ds_read_b128 v[50:53], v83 offset:23104
	ds_read_b128 v[54:57], v83 offset:25600
	ds_read_b128 v[68:71], v83 offset:25664
	ds_read_b128 v[78:81], v83 offset:28160
	ds_read_b128 v[84:87], v83 offset:28224
	s_setprio 1
	s_waitcnt lgkmcnt(7)
	v_mfma_f32_16x16x32_bf16 v[88:91], v[26:29], v[6:9], 0
	v_mfma_f32_16x16x32_bf16 v[102:105], v[26:29], v[14:17], 0
	s_waitcnt lgkmcnt(5)
	v_mfma_f32_16x16x32_bf16 v[110:113], v[42:45], v[6:9], 0
	v_mfma_f32_16x16x32_bf16 v[42:45], v[42:45], v[14:17], 0
	s_waitcnt lgkmcnt(3)
	v_mfma_f32_16x16x32_bf16 v[114:117], v[54:57], v[6:9], 0
	v_mfma_f32_16x16x32_bf16 v[118:121], v[54:57], v[14:17], 0
	s_waitcnt lgkmcnt(1)
	v_mfma_f32_16x16x32_bf16 v[122:125], v[78:81], v[6:9], 0
	v_mfma_f32_16x16x32_bf16 v[78:81], v[78:81], v[14:17], 0
	v_mfma_f32_16x16x32_bf16 v[26:29], v[34:37], v[2:5], v[88:91]
	v_mfma_f32_16x16x32_bf16 v[54:57], v[34:37], v[10:13], v[102:105]
	v_mfma_f32_16x16x32_bf16 v[34:37], v[50:53], v[2:5], v[110:113]
	v_mfma_f32_16x16x32_bf16 v[126:129], v[50:53], v[10:13], v[42:45]
	v_mfma_f32_16x16x32_bf16 v[42:45], v[68:71], v[2:5], v[114:117]
	v_mfma_f32_16x16x32_bf16 v[102:105], v[68:71], v[10:13], v[118:121]
	s_waitcnt lgkmcnt(0)
	v_mfma_f32_16x16x32_bf16 v[50:53], v[84:87], v[2:5], v[122:125]
	v_mfma_f32_16x16x32_bf16 v[70:73], v[84:87], v[10:13], v[78:81]
	s_setprio 0
	v_lshlrev_b32_e32 v160, 2, v82
	s_nop 0
	v_or_b32_e32 v80, 0x71, v160
	v_or_b32_e32 v81, 0x70, v160
	v_subrev_u32_e32 v124, 63, v158
	v_lshlrev_b32_e32 v68, 6, v80
	v_lshlrev_b32_e32 v69, 6, v81
	v_sub_u32_e32 v78, v124, v69
	v_sub_u32_e32 v68, v124, v68
	v_cvt_f32_i32_e32 v69, v68
	v_cvt_f32_i32_e32 v68, v78
	v_or_b32_e32 v83, 0x73, v160
	v_or_b32_e32 v84, 0x72, v160
	v_cmp_lt_i32_e32 vcc, v80, v130
	v_pk_fma_f32 v[78:79], v[148:149], v[68:69], v[70:71] op_sel_hi:[0,1,1] neg_lo:[1,0,0] neg_hi:[1,0,0]
	v_lshlrev_b32_e32 v70, 6, v83
	v_lshlrev_b32_e32 v71, 6, v84
	v_sub_u32_e32 v85, v124, v71
	v_sub_u32_e32 v70, v124, v70
	v_cvt_f32_i32_e32 v71, v70
	v_cvt_f32_i32_e32 v70, v85
	v_cmp_lt_i32_e64 s[0:1], v81, v130
	v_or_b32_e32 v80, 49, v160
	v_or_b32_e32 v81, 48, v160
	v_cndmask_b32_e32 v85, v173, v79, vcc
	v_cndmask_b32_e64 v86, v173, v78, s[0:1]
	v_pk_fma_f32 v[78:79], v[148:149], v[70:71], v[72:73] op_sel_hi:[0,1,1] neg_lo:[1,0,0] neg_hi:[1,0,0]
	v_lshlrev_b32_e32 v72, 6, v80
	v_lshlrev_b32_e32 v73, 6, v81
	v_sub_u32_e32 v87, v124, v73
	v_sub_u32_e32 v72, v124, v72
	v_cvt_f32_i32_e32 v73, v72
	v_cvt_f32_i32_e32 v72, v87
	v_cmp_lt_i32_e64 s[8:9], v83, v130
	v_cmp_lt_i32_e64 s[12:13], v84, v130
	v_or_b32_e32 v87, 51, v160
	v_or_b32_e32 v91, 50, v160
	v_cndmask_b32_e64 v83, v173, v79, s[8:9]
	v_cndmask_b32_e64 v84, v173, v78, s[12:13]
	v_pk_fma_f32 v[78:79], v[148:149], v[72:73], v[74:75] op_sel_hi:[0,1,1] neg_lo:[1,0,0] neg_hi:[1,0,0]
	v_lshlrev_b32_e32 v74, 6, v87
	v_lshlrev_b32_e32 v75, 6, v91
	v_sub_u32_e32 v88, v124, v75
	v_sub_u32_e32 v74, v124, v74
	v_cvt_f32_i32_e32 v75, v74
	v_cvt_f32_i32_e32 v74, v88
	v_cmp_lt_i32_e64 s[14:15], v80, v130
	v_cmp_lt_i32_e64 s[16:17], v81, v130
	v_or_b32_e32 v101, 0x61, v160
	v_or_b32_e32 v106, 0x60, v160
	v_cndmask_b32_e64 v90, v173, v79, s[14:15]
	v_cndmask_b32_e64 v88, v173, v78, s[16:17]
	v_pk_fma_f32 v[78:79], v[148:149], v[74:75], v[76:77] op_sel_hi:[0,1,1] neg_lo:[1,0,0] neg_hi:[1,0,0]
	v_lshlrev_b32_e32 v76, 6, v101
	v_lshlrev_b32_e32 v77, 6, v106
	v_sub_u32_e32 v80, v124, v77
	v_sub_u32_e32 v76, v124, v76
	v_cvt_f32_i32_e32 v77, v76
	v_cvt_f32_i32_e32 v76, v80
	v_cmp_lt_i32_e64 s[18:19], v87, v130
	v_cmp_lt_i32_e64 s[20:21], v91, v130
	v_or_b32_e32 v91, 0x63, v160
	v_or_b32_e32 v107, 0x62, v160
	v_cndmask_b32_e64 v89, v173, v79, s[18:19]
	v_cndmask_b32_e64 v87, v173, v78, s[20:21]
	v_lshlrev_b32_e32 v78, 6, v91
	v_lshlrev_b32_e32 v79, 6, v107
	v_pk_fma_f32 v[80:81], v[148:149], v[76:77], v[102:103] op_sel_hi:[0,1,1] neg_lo:[1,0,0] neg_hi:[1,0,0]
	v_sub_u32_e32 v102, v124, v79
	v_sub_u32_e32 v78, v124, v78
	v_cvt_f32_i32_e32 v79, v78
	v_cvt_f32_i32_e32 v78, v102
	v_cmp_lt_i32_e64 s[22:23], v101, v130
	v_cmp_lt_i32_e64 s[24:25], v106, v130
	v_or_b32_e32 v106, 33, v160
	v_or_b32_e32 v109, 32, v160
	v_cndmask_b32_e64 v102, v173, v81, s[22:23]
	v_cndmask_b32_e64 v103, v173, v80, s[24:25]
	v_lshlrev_b32_e32 v80, 6, v106
	v_lshlrev_b32_e32 v81, 6, v109
	v_pk_fma_f32 v[104:105], v[148:149], v[78:79], v[104:105] op_sel_hi:[0,1,1] neg_lo:[1,0,0] neg_hi:[1,0,0]
	v_sub_u32_e32 v101, v124, v81
	v_sub_u32_e32 v80, v124, v80
	v_cmp_lt_i32_e64 s[28:29], v107, v130
	v_cvt_f32_i32_e32 v81, v80
	v_cvt_f32_i32_e32 v80, v101
	v_cmp_lt_i32_e64 s[26:27], v91, v130
	v_cndmask_b32_e64 v101, v173, v104, s[28:29]
	v_or_b32_e32 v104, 35, v160
	v_or_b32_e32 v110, 34, v160
	v_cndmask_b32_e64 v91, v173, v105, s[26:27]
	v_lshlrev_b32_e32 v105, 6, v104
	v_lshlrev_b32_e32 v107, 6, v110
	v_sub_u32_e32 v107, v124, v107
	v_sub_u32_e32 v105, v124, v105
	v_cvt_f32_i32_e32 v115, v105
	v_cvt_f32_i32_e32 v114, v107
	v_pk_fma_f32 v[92:93], v[148:149], v[80:81], v[92:93] op_sel_hi:[0,1,1] neg_lo:[1,0,0] neg_hi:[1,0,0]
	v_cmp_lt_i32_e64 s[30:31], v106, v130
	v_cmp_lt_i32_e64 s[34:35], v109, v130
	v_or_b32_e32 v109, 0x51, v160
	v_or_b32_e32 v112, 0x50, v160
	v_cndmask_b32_e64 v107, v173, v93, s[30:31]
	v_cndmask_b32_e64 v105, v173, v92, s[34:35]
	v_pk_fma_f32 v[92:93], v[148:149], v[114:115], v[94:95] op_sel_hi:[0,1,1] neg_lo:[1,0,0] neg_hi:[1,0,0]
	v_lshlrev_b32_e32 v94, 6, v109
	v_lshlrev_b32_e32 v95, 6, v112
	v_cmp_lt_i32_e64 s[38:39], v110, v130
	v_or_b32_e32 v110, 0x53, v160
	v_or_b32_e32 v113, 0x52, v160
	v_sub_u32_e32 v106, v124, v95
	v_sub_u32_e32 v94, v124, v94
	v_lshlrev_b32_e32 v111, 6, v110
	v_lshlrev_b32_e32 v116, 6, v113
	v_cvt_f32_i32_e32 v95, v94
	v_cvt_f32_i32_e32 v94, v106
	v_sub_u32_e32 v116, v124, v116
	v_sub_u32_e32 v111, v124, v111
	v_cvt_f32_i32_e32 v117, v111
	v_cvt_f32_i32_e32 v116, v116
	v_cmp_lt_i32_e64 s[36:37], v104, v130
	v_or_b32_e32 v120, 17, v160
	v_cndmask_b32_e64 v104, v173, v92, s[38:39]
	v_cndmask_b32_e64 v106, v173, v93, s[36:37]
	v_pk_fma_f32 v[92:93], v[148:149], v[94:95], v[126:127] op_sel_hi:[0,1,1] neg_lo:[1,0,0] neg_hi:[1,0,0]
	v_cmp_lt_i32_e64 s[40:41], v109, v130
	v_cmp_lt_i32_e64 s[42:43], v112, v130
	v_lshlrev_b32_e32 v109, 6, v120
	v_cndmask_b32_e64 v111, v173, v93, s[40:41]
	v_cndmask_b32_e64 v112, v173, v92, s[42:43]
	v_pk_fma_f32 v[92:93], v[148:149], v[116:117], v[128:129] op_sel_hi:[0,1,1] neg_lo:[1,0,0] neg_hi:[1,0,0]
	v_or_b32_e32 v121, 16, v160
	v_sub_u32_e32 v109, v124, v109
	v_cmp_lt_i32_e64 s[44:45], v110, v130
	v_cmp_lt_i32_e64 s[46:47], v113, v130
	v_or_b32_e32 v126, 19, v160
	v_or_b32_e32 v127, 18, v160
	v_lshlrev_b32_e32 v118, 6, v121
	v_cvt_f32_i32_e32 v119, v109
	v_cndmask_b32_e64 v109, v173, v93, s[44:45]
	v_cndmask_b32_e64 v110, v173, v92, s[46:47]
	v_lshlrev_b32_e32 v92, 6, v126
	v_lshlrev_b32_e32 v93, 6, v127
	v_sub_u32_e32 v118, v124, v118
	v_sub_u32_e32 v113, v124, v93
	v_sub_u32_e32 v92, v124, v92
	v_cvt_f32_i32_e32 v118, v118
	v_cvt_f32_i32_e32 v93, v92
	v_cvt_f32_i32_e32 v92, v113
	v_cmp_lt_i32_e64 s[48:49], v120, v130
	v_pk_fma_f32 v[58:59], v[148:149], v[118:119], v[58:59] op_sel_hi:[0,1,1] neg_lo:[1,0,0] neg_hi:[1,0,0]
	v_cmp_lt_i32_e64 s[50:51], v121, v130
	v_pk_fma_f32 v[120:121], v[148:149], v[92:93], v[60:61] op_sel_hi:[0,1,1] neg_lo:[1,0,0] neg_hi:[1,0,0]
	v_or_b32_e32 v61, 0x41, v160
	v_or_b32_e32 v128, 64, v160
	v_cndmask_b32_e64 v113, v173, v59, s[48:49]
	v_cndmask_b32_e64 v59, v173, v58, s[50:51]
	v_lshlrev_b32_e32 v58, 6, v61
	v_lshlrev_b32_e32 v60, 6, v128
	v_sub_u32_e32 v60, v124, v60
	v_sub_u32_e32 v58, v124, v58
	v_cmp_lt_i32_e64 s[52:53], v126, v130
	v_cmp_lt_i32_e64 s[54:55], v127, v130
	v_or_b32_e32 v126, 0x43, v160
	v_or_b32_e32 v127, 0x42, v160
	v_cvt_f32_i32_e32 v123, v58
	v_cvt_f32_i32_e32 v122, v60
	v_cndmask_b32_e64 v60, v173, v121, s[52:53]
	v_cndmask_b32_e64 v58, v173, v120, s[54:55]
	v_lshlrev_b32_e32 v120, 6, v126
	v_lshlrev_b32_e32 v121, 6, v127
	v_sub_u32_e32 v129, v124, v121
	v_sub_u32_e32 v120, v124, v120
	v_cvt_f32_i32_e32 v121, v120
	v_cvt_f32_i32_e32 v120, v129
	v_or_b32_e32 v125, 1, v160
	v_pk_fma_f32 v[54:55], v[148:149], v[122:123], v[54:55] op_sel_hi:[0,1,1] neg_lo:[1,0,0] neg_hi:[1,0,0]
	v_cmp_lt_i32_e64 s[56:57], v61, v130
	v_cmp_lt_i32_e64 s[58:59], v128, v130
	v_cmp_lt_i32_e64 s[62:63], v127, v130
	v_cndmask_b32_e64 v61, v173, v55, s[56:57]
	v_cndmask_b32_e64 v128, v173, v54, s[58:59]
	v_pk_fma_f32 v[54:55], v[148:149], v[120:121], v[56:57] op_sel_hi:[0,1,1] neg_lo:[1,0,0] neg_hi:[1,0,0]
	v_lshlrev_b32_e32 v56, 6, v125
	v_lshlrev_b32_e32 v57, 8, v82
	v_sub_u32_e32 v82, v124, v57
	v_sub_u32_e32 v56, v124, v56
	v_cvt_f32_i32_e32 v57, v56
	v_cvt_f32_i32_e32 v56, v82
	v_cmp_lt_i32_e64 s[64:65], v125, v130
	v_or_b32_e32 v127, 3, v160
	v_or_b32_e32 v129, 2, v160
	v_pk_fma_f32 v[46:47], v[148:149], v[56:57], v[46:47] op_sel_hi:[0,1,1] neg_lo:[1,0,0] neg_hi:[1,0,0]
	v_cmp_lt_i32_e64 s[60:61], v126, v130
	v_cndmask_b32_e64 v126, v173, v54, s[62:63]
	v_cndmask_b32_e64 v125, v173, v47, s[64:65]
	v_lshlrev_b32_e32 v47, 6, v127
	v_lshlrev_b32_e32 v54, 6, v129
	v_sub_u32_e32 v54, v124, v54
	v_sub_u32_e32 v47, v124, v47
	v_cndmask_b32_e64 v82, v173, v55, s[60:61]
	v_cvt_f32_i32_e32 v55, v47
	v_cvt_f32_i32_e32 v54, v54
	v_cmp_lt_i32_e64 s[66:67], v160, v130
	v_cmp_lt_i32_e64 s[70:71], v129, v130
	v_cmp_lt_i32_e64 s[68:69], v127, v130
	v_cndmask_b32_e64 v124, v173, v46, s[66:67]
	v_max3_f32 v46, v124, s96, v128
	v_max3_f32 v131, v46, v125, v61
	v_pk_fma_f32 v[46:47], v[148:149], v[54:55], v[48:49] op_sel_hi:[0,1,1] neg_lo:[1,0,0] neg_hi:[1,0,0]
	v_cndmask_b32_e64 v129, v173, v46, s[70:71]
	v_cndmask_b32_e64 v127, v173, v47, s[68:69]
	v_max3_f32 v46, v131, v129, v126
	v_max3_f32 v46, v46, v127, v82
	v_max3_f32 v46, v46, v59, v112
	v_max3_f32 v46, v46, v113, v111
	v_max3_f32 v46, v46, v58, v110
	v_max3_f32 v46, v46, v60, v109
	v_max3_f32 v46, v46, v105, v103
	v_max3_f32 v46, v46, v107, v102
	v_max3_f32 v46, v46, v104, v101
	v_max3_f32 v46, v46, v106, v91
	v_max3_f32 v46, v46, v88, v86
	v_max3_f32 v48, v46, v90, v85
	v_pk_fma_f32 v[46:47], v[146:147], v[68:69], v[50:51] op_sel_hi:[0,1,1] neg_lo:[1,0,0] neg_hi:[1,0,0]
	v_cndmask_b32_e32 v49, v173, v47, vcc
	v_cndmask_b32_e64 v50, v173, v46, s[0:1]
	v_pk_fma_f32 v[46:47], v[146:147], v[70:71], v[52:53] op_sel_hi:[0,1,1] neg_lo:[1,0,0] neg_hi:[1,0,0]
	v_pk_fma_f32 v[38:39], v[146:147], v[72:73], v[38:39] op_sel_hi:[0,1,1] neg_lo:[1,0,0] neg_hi:[1,0,0]
	v_cndmask_b32_e64 v51, v173, v47, s[8:9]
	v_cndmask_b32_e64 v52, v173, v46, s[12:13]
	v_cndmask_b32_e64 v46, v173, v39, s[14:15]
	v_cndmask_b32_e64 v47, v173, v38, s[16:17]
	v_pk_fma_f32 v[38:39], v[146:147], v[74:75], v[40:41] op_sel_hi:[0,1,1] neg_lo:[1,0,0] neg_hi:[1,0,0]
	v_cndmask_b32_e64 v53, v173, v39, s[18:19]
	v_cndmask_b32_e64 v68, v173, v38, s[20:21]
	v_pk_fma_f32 v[38:39], v[146:147], v[76:77], v[42:43] op_sel_hi:[0,1,1] neg_lo:[1,0,0] neg_hi:[1,0,0]
	v_cndmask_b32_e64 v40, v173, v39, s[22:23]
	v_cndmask_b32_e64 v41, v173, v38, s[24:25]
	v_pk_fma_f32 v[38:39], v[146:147], v[78:79], v[44:45] op_sel_hi:[0,1,1] neg_lo:[1,0,0] neg_hi:[1,0,0]
	v_pk_fma_f32 v[30:31], v[146:147], v[80:81], v[30:31] op_sel_hi:[0,1,1] neg_lo:[1,0,0] neg_hi:[1,0,0]
	v_cndmask_b32_e64 v42, v173, v39, s[26:27]
	v_cndmask_b32_e64 v44, v173, v38, s[28:29]
	v_cndmask_b32_e64 v38, v173, v31, s[30:31]
	v_cndmask_b32_e64 v39, v173, v30, s[34:35]
	v_pk_fma_f32 v[30:31], v[146:147], v[114:115], v[32:33] op_sel_hi:[0,1,1] neg_lo:[1,0,0] neg_hi:[1,0,0]
	v_cndmask_b32_e64 v43, v173, v31, s[36:37]
	v_cndmask_b32_e64 v45, v173, v30, s[38:39]
	v_pk_fma_f32 v[30:31], v[146:147], v[94:95], v[34:35] op_sel_hi:[0,1,1] neg_lo:[1,0,0] neg_hi:[1,0,0]
	v_pk_fma_f32 v[22:23], v[146:147], v[118:119], v[22:23] op_sel_hi:[0,1,1] neg_lo:[1,0,0] neg_hi:[1,0,0]
	v_cndmask_b32_e64 v32, v173, v31, s[40:41]
	v_cndmask_b32_e64 v33, v173, v30, s[42:43]
	v_pk_fma_f32 v[30:31], v[146:147], v[116:117], v[36:37] op_sel_hi:[0,1,1] neg_lo:[1,0,0] neg_hi:[1,0,0]
	v_cndmask_b32_e64 v35, v173, v23, s[48:49]
	v_cndmask_b32_e64 v37, v173, v22, s[50:51]
	v_pk_fma_f32 v[22:23], v[146:147], v[92:93], v[24:25] op_sel_hi:[0,1,1] neg_lo:[1,0,0] neg_hi:[1,0,0]
	v_cndmask_b32_e64 v69, v173, v23, s[52:53]
	v_cndmask_b32_e64 v70, v173, v22, s[54:55]
	v_pk_fma_f32 v[22:23], v[146:147], v[122:123], v[26:27] op_sel_hi:[0,1,1] neg_lo:[1,0,0] neg_hi:[1,0,0]
	v_pk_fma_f32 v[18:19], v[146:147], v[56:57], v[18:19] op_sel_hi:[0,1,1] neg_lo:[1,0,0] neg_hi:[1,0,0]
	v_cndmask_b32_e64 v24, v173, v23, s[56:57]
	v_cndmask_b32_e64 v25, v173, v22, s[58:59]
	v_pk_fma_f32 v[22:23], v[146:147], v[120:121], v[28:29] op_sel_hi:[0,1,1] neg_lo:[1,0,0] neg_hi:[1,0,0]
	v_cndmask_b32_e64 v28, v173, v18, s[66:67]
	v_cndmask_b32_e64 v26, v173, v19, s[64:65]
	v_max3_f32 v18, v28, s96, v25
	v_max3_f32 v27, v18, v26, v24
	v_pk_fma_f32 v[18:19], v[146:147], v[54:55], v[20:21] op_sel_hi:[0,1,1] neg_lo:[1,0,0] neg_hi:[1,0,0]
	v_cndmask_b32_e64 v22, v173, v22, s[62:63]
	v_cndmask_b32_e64 v21, v173, v18, s[70:71]
	v_cndmask_b32_e64 v23, v173, v23, s[60:61]
	v_cndmask_b32_e64 v20, v173, v19, s[68:69]
	v_max3_f32 v18, v27, v21, v22
	v_max3_f32 v18, v18, v20, v23
	v_max3_f32 v18, v18, v37, v33
	v_cndmask_b32_e64 v36, v173, v30, s[46:47]
	v_max3_f32 v18, v18, v35, v32
	v_cndmask_b32_e64 v34, v173, v31, s[44:45]
	v_max3_f32 v18, v18, v70, v36
	v_max3_f32 v18, v18, v69, v34
	v_max3_f32 v18, v18, v39, v41
	v_max3_f32 v18, v18, v38, v40
	v_max3_f32 v18, v18, v45, v44
	v_max3_f32 v18, v18, v43, v42
	v_max3_f32 v18, v18, v47, v50
	v_max3_f32 v18, v18, v46, v49
	v_max3_f32 v18, v18, v68, v52
	v_max3_f32 v18, v18, v53, v51
	v_mov_b32_e32 v19, v18
	s_nop 1
	v_permlane16_swap_b32_e32 v18, v19
	v_max_f32_e32 v19, v19, v19
	v_max_f32_e32 v18, v18, v18
	v_max_f32_e32 v18, v18, v19
	v_mov_b32_e32 v19, v18
	s_nop 1
	v_permlane32_swap_b32_e32 v18, v19
	v_max_f32_e32 v19, v19, v19
	v_max_f32_e32 v18, v18, v18
	v_max_f32_e32 v54, v18, v19
	v_sub_f32_e32 v19, v26, v54
	v_exp_f32_e32 v19, v19
	v_sub_f32_e32 v18, v28, v54
	v_sub_f32_e32 v27, v25, v54
	v_cmp_lt_f32_e32 vcc, s97, v26
	v_exp_f32_e32 v18, v18
	v_exp_f32_e32 v29, v27
	v_cndmask_b32_e32 v27, 0, v19, vcc
	v_sub_f32_e32 v19, v24, v54
	v_exp_f32_e32 v19, v19
	v_cmp_lt_f32_e32 vcc, s97, v28
	v_and_b32_e32 v166, 24, v156
	s_mov_b32 s26, s7
	v_cndmask_b32_e32 v26, 0, v18, vcc
	v_cmp_lt_f32_e32 vcc, s97, v24
	s_nop 1
	v_cndmask_b32_e32 v31, 0, v19, vcc
	v_cmp_lt_f32_e32 vcc, s97, v25
	v_sub_f32_e32 v25, v22, v54
	v_exp_f32_e32 v25, v25
	v_cndmask_b32_e32 v30, 0, v29, vcc
	v_pk_add_f32 v[18:19], v[26:27], v[30:31]
	v_cmp_lt_f32_e32 vcc, s97, v20
	v_add_f32_e32 v18, 0, v18
	v_add_f32_e32 v24, v19, v18
	v_sub_f32_e32 v19, v20, v54
	v_sub_f32_e32 v18, v21, v54
	v_exp_f32_e32 v19, v19
	v_exp_f32_e32 v18, v18
	v_sub_f32_e32 v20, v23, v54
	v_exp_f32_e32 v20, v20
	v_cndmask_b32_e32 v19, 0, v19, vcc
	v_cmp_lt_f32_e32 vcc, s97, v21
	s_nop 1
	v_cndmask_b32_e32 v18, 0, v18, vcc
	v_cmp_lt_f32_e32 vcc, s97, v23
	s_nop 1
	v_cndmask_b32_e32 v21, 0, v20, vcc
	v_cmp_lt_f32_e32 vcc, s97, v22
	s_nop 1
	v_cndmask_b32_e32 v20, 0, v25, vcc
	v_pk_add_f32 v[22:23], v[18:19], v[20:21]
	v_sub_f32_e32 v25, v32, v54
	v_add_f32_e32 v22, v22, v24
	v_add_f32_e32 v55, v23, v22
	v_sub_f32_e32 v23, v35, v54
	v_sub_f32_e32 v22, v37, v54
	v_exp_f32_e32 v23, v23
	v_exp_f32_e32 v22, v22
	v_sub_f32_e32 v24, v33, v54
	v_exp_f32_e32 v25, v25
	v_exp_f32_e32 v24, v24
	v_cmp_lt_f32_e32 vcc, s97, v35
	s_nop 1
	v_cndmask_b32_e32 v23, 0, v23, vcc
	v_cmp_lt_f32_e32 vcc, s97, v37
	s_nop 1
	v_cndmask_b32_e32 v22, 0, v22, vcc
	v_cmp_lt_f32_e32 vcc, s97, v32
	v_sub_f32_e32 v32, v36, v54
	v_exp_f32_e32 v32, v32
	v_cndmask_b32_e32 v25, 0, v25, vcc
	v_cmp_lt_f32_e32 vcc, s97, v33
	v_sub_f32_e32 v33, v34, v54
	v_exp_f32_e32 v33, v33
	v_cndmask_b32_e32 v24, 0, v24, vcc
	v_pk_add_f32 v[28:29], v[22:23], v[24:25]
	v_cmp_lt_f32_e32 vcc, s97, v69
	v_add_f32_e32 v28, v28, v55
	v_add_f32_e32 v37, v29, v28
	v_sub_f32_e32 v29, v69, v54
	v_sub_f32_e32 v28, v70, v54
	v_exp_f32_e32 v29, v29
	v_exp_f32_e32 v28, v28
	v_cndmask_b32_e32 v29, 0, v29, vcc
	v_cmp_lt_f32_e32 vcc, s97, v70
	s_nop 1
	v_cndmask_b32_e32 v28, 0, v28, vcc
	v_cmp_lt_f32_e32 vcc, s97, v34
	s_nop 1
	v_cndmask_b32_e32 v35, 0, v33, vcc
	v_cmp_lt_f32_e32 vcc, s97, v36
	v_sub_f32_e32 v36, v41, v54
	v_exp_f32_e32 v36, v36
	v_cndmask_b32_e32 v34, 0, v32, vcc
	v_pk_add_f32 v[32:33], v[28:29], v[34:35]
	v_cmp_lt_f32_e32 vcc, s97, v38
	v_add_f32_e32 v32, v32, v37
	v_add_f32_e32 v55, v33, v32
	v_sub_f32_e32 v33, v38, v54
	v_sub_f32_e32 v32, v39, v54
	v_exp_f32_e32 v33, v33
	v_exp_f32_e32 v32, v32
	v_sub_f32_e32 v37, v40, v54
	v_exp_f32_e32 v37, v37
	v_cndmask_b32_e32 v33, 0, v33, vcc
	v_cmp_lt_f32_e32 vcc, s97, v39
	s_nop 1
	v_cndmask_b32_e32 v32, 0, v32, vcc
	v_cmp_lt_f32_e32 vcc, s97, v40
	v_sub_f32_e32 v40, v44, v54
	v_exp_f32_e32 v40, v40
	v_cndmask_b32_e32 v37, 0, v37, vcc
	v_cmp_lt_f32_e32 vcc, s97, v41
	v_sub_f32_e32 v41, v42, v54
	v_exp_f32_e32 v41, v41
	v_cndmask_b32_e32 v36, 0, v36, vcc
	v_pk_add_f32 v[38:39], v[32:33], v[36:37]
	v_cmp_lt_f32_e32 vcc, s97, v43
	v_add_f32_e32 v38, v38, v55
	v_add_f32_e32 v55, v39, v38
	v_sub_f32_e32 v39, v43, v54
	v_sub_f32_e32 v38, v45, v54
	v_exp_f32_e32 v39, v39
	v_exp_f32_e32 v38, v38
	v_cndmask_b32_e32 v39, 0, v39, vcc
	v_cmp_lt_f32_e32 vcc, s97, v45
	v_sub_f32_e32 v45, v49, v54
	v_exp_f32_e32 v45, v45
	v_cndmask_b32_e32 v38, 0, v38, vcc
	v_cmp_lt_f32_e32 vcc, s97, v42
	s_nop 1
	v_cndmask_b32_e32 v43, 0, v41, vcc
	v_cmp_lt_f32_e32 vcc, s97, v44
	v_sub_f32_e32 v44, v50, v54
	v_exp_f32_e32 v44, v44
	v_cndmask_b32_e32 v42, 0, v40, vcc
	v_pk_add_f32 v[40:41], v[38:39], v[42:43]
	v_cmp_lt_f32_e32 vcc, s97, v46
	v_add_f32_e32 v40, v40, v55
	v_add_f32_e32 v55, v41, v40
	v_sub_f32_e32 v41, v46, v54
	v_sub_f32_e32 v40, v47, v54
	v_exp_f32_e32 v41, v41
	v_exp_f32_e32 v40, v40
	v_cndmask_b32_e32 v41, 0, v41, vcc
	v_cmp_lt_f32_e32 vcc, s97, v47
	s_nop 1
	v_cndmask_b32_e32 v40, 0, v40, vcc
	v_cmp_lt_f32_e32 vcc, s97, v49
	s_nop 1
	v_cndmask_b32_e32 v45, 0, v45, vcc
	v_cmp_lt_f32_e32 vcc, s97, v50
	v_sub_f32_e32 v50, v52, v54
	v_exp_f32_e32 v50, v50
	v_cndmask_b32_e32 v44, 0, v44, vcc
	v_pk_add_f32 v[46:47], v[40:41], v[44:45]
	v_cmp_lt_f32_e32 vcc, s97, v53
	v_add_f32_e32 v46, v46, v55
	v_add_f32_e32 v49, v47, v46
	v_sub_f32_e32 v47, v53, v54
	v_exp_f32_e32 v47, v47
	v_sub_f32_e32 v46, v68, v54
	v_exp_f32_e32 v46, v46
	v_cndmask_b32_e32 v93, 0, v47, vcc
	v_sub_f32_e32 v47, v51, v54
	v_exp_f32_e32 v47, v47
	v_cmp_lt_f32_e32 vcc, s97, v68
	s_nop 1
	v_cndmask_b32_e32 v92, 0, v46, vcc
	v_cmp_lt_f32_e32 vcc, s97, v51
	s_nop 1
	v_cndmask_b32_e32 v95, 0, v47, vcc
	v_cmp_lt_f32_e32 vcc, s97, v52
	s_nop 1
	v_cndmask_b32_e32 v94, 0, v50, vcc
	v_pk_add_f32 v[46:47], v[92:93], v[94:95]
	v_cmp_lt_f32_e32 vcc, s97, v125
	v_add_f32_e32 v46, v46, v49
	v_add_f32_e32 v46, v47, v46
	v_mov_b32_e32 v47, v46
	s_nop 1
	v_permlane16_swap_b32_e32 v46, v47
	v_add_f32_e32 v51, v46, v47
	v_max3_f32 v46, v48, v87, v84
	v_max3_f32 v46, v46, v89, v83
	v_mov_b32_e32 v47, v46
	s_nop 1
	v_permlane16_swap_b32_e32 v46, v47
	v_max_f32_e32 v47, v47, v47
	v_max_f32_e32 v46, v46, v46
	v_max_f32_e32 v46, v46, v47
	v_mov_b32_e32 v47, v46
	s_nop 1
	v_permlane32_swap_b32_e32 v46, v47
	v_max_f32_e32 v47, v47, v47
	v_max_f32_e32 v46, v46, v46
	v_max_f32_e32 v50, v46, v47
	v_sub_f32_e32 v47, v125, v50
	v_sub_f32_e32 v46, v124, v50
	v_exp_f32_e32 v47, v47
	v_exp_f32_e32 v46, v46
	v_sub_f32_e32 v49, v61, v50
	v_sub_f32_e32 v48, v128, v50
	v_exp_f32_e32 v49, v49
	v_exp_f32_e32 v48, v48
	v_cndmask_b32_e32 v47, 0, v47, vcc
	v_cmp_lt_f32_e32 vcc, s97, v124
	v_sub_f32_e32 v57, v82, v50
	v_sub_f32_e32 v56, v126, v50
	v_cndmask_b32_e32 v46, 0, v46, vcc
	v_cmp_lt_f32_e32 vcc, s97, v61
	v_exp_f32_e32 v57, v57
	v_exp_f32_e32 v56, v56
	v_cndmask_b32_e32 v49, 0, v49, vcc
	v_cmp_lt_f32_e32 vcc, s97, v128
	v_sub_f32_e32 v61, v59, v50
	v_exp_f32_e32 v61, v61
	v_cndmask_b32_e32 v48, 0, v48, vcc
	v_pk_add_f32 v[54:55], v[46:47], v[48:49]
	v_cmp_lt_f32_e32 vcc, s97, v127
	v_add_f32_e32 v52, 0, v54
	v_add_f32_e32 v52, v55, v52
	v_sub_f32_e32 v55, v127, v50
	v_sub_f32_e32 v54, v129, v50
	v_exp_f32_e32 v55, v55
	v_exp_f32_e32 v54, v54
	v_sub_f32_e32 v75, v102, v50
	v_sub_f32_e32 v74, v103, v50
	v_cndmask_b32_e32 v55, 0, v55, vcc
	v_cmp_lt_f32_e32 vcc, s97, v129
	v_exp_f32_e32 v75, v75
	v_exp_f32_e32 v74, v74
	v_cndmask_b32_e32 v54, 0, v54, vcc
	v_cmp_lt_f32_e32 vcc, s97, v82
	v_sub_f32_e32 v79, v91, v50
	v_sub_f32_e32 v78, v101, v50
	v_cndmask_b32_e32 v57, 0, v57, vcc
	v_cmp_lt_f32_e32 vcc, s97, v126
	v_exp_f32_e32 v79, v79
	v_exp_f32_e32 v78, v78
	v_cndmask_b32_e32 v56, 0, v56, vcc
	v_pk_add_f32 v[68:69], v[54:55], v[56:57]
	v_cmp_lt_f32_e32 vcc, s97, v113
	v_add_f32_e32 v52, v68, v52
	v_sub_f32_e32 v68, v113, v50
	v_exp_f32_e32 v68, v68
	v_add_f32_e32 v52, v69, v52
	v_sub_f32_e32 v69, v112, v50
	v_exp_f32_e32 v70, v69
	v_cndmask_b32_e32 v69, 0, v68, vcc
	v_sub_f32_e32 v68, v111, v50
	v_exp_f32_e32 v71, v68
	v_cmp_lt_f32_e32 vcc, s97, v59
	v_sub_f32_e32 v59, v58, v50
	v_sub_f32_e32 v82, v86, v50
	v_cndmask_b32_e32 v68, 0, v61, vcc
	v_cmp_lt_f32_e32 vcc, s97, v111
	v_exp_f32_e32 v61, v59
	v_sub_f32_e32 v59, v60, v50
	v_cndmask_b32_e32 v71, 0, v71, vcc
	v_cmp_lt_f32_e32 vcc, s97, v112
	v_exp_f32_e32 v59, v59
	v_exp_f32_e32 v82, v82
	v_cndmask_b32_e32 v70, 0, v70, vcc
	v_pk_add_f32 v[72:73], v[68:69], v[70:71]
	v_cmp_lt_f32_e32 vcc, s97, v60
	v_sub_f32_e32 v60, v109, v50
	v_add_f32_e32 v52, v72, v52
	v_sub_f32_e32 v72, v110, v50
	v_exp_f32_e32 v60, v60
	v_exp_f32_e32 v72, v72
	v_cndmask_b32_e32 v59, 0, v59, vcc
	v_cmp_lt_f32_e32 vcc, s97, v58
	v_add_f32_e32 v52, v73, v52
	v_mov_b32_e32 v53, v51
	v_cndmask_b32_e32 v58, 0, v61, vcc
	v_cmp_lt_f32_e32 vcc, s97, v109
	v_permlane32_swap_b32_e32 v51, v53
	s_nop 0
	v_cndmask_b32_e32 v61, 0, v60, vcc
	v_cmp_lt_f32_e32 vcc, s97, v110
	v_mov_b32_e32 v110, v165
	v_mov_b32_e32 v111, v165
	v_cndmask_b32_e32 v60, 0, v72, vcc
	v_pk_add_f32 v[72:73], v[58:59], v[60:61]
	v_cmp_lt_f32_e32 vcc, s97, v107
	v_add_f32_e32 v52, v72, v52
	v_add_f32_e32 v52, v73, v52
	v_sub_f32_e32 v73, v107, v50
	v_sub_f32_e32 v72, v105, v50
	v_exp_f32_e32 v73, v73
	v_exp_f32_e32 v72, v72
	v_cndmask_b32_e32 v73, 0, v73, vcc
	v_cmp_lt_f32_e32 vcc, s97, v105
	v_mov_b32_e32 v105, v165
	s_nop 0
	v_cndmask_b32_e32 v72, 0, v72, vcc
	v_cmp_lt_f32_e32 vcc, s97, v102
	s_nop 1
	v_cndmask_b32_e32 v75, 0, v75, vcc
	v_cmp_lt_f32_e32 vcc, s97, v103
	s_nop 1
	v_cndmask_b32_e32 v74, 0, v74, vcc
	v_pk_add_f32 v[76:77], v[72:73], v[74:75]
	v_cmp_lt_f32_e32 vcc, s97, v106
	v_add_f32_e32 v52, v76, v52
	v_add_f32_e32 v52, v77, v52
	v_sub_f32_e32 v77, v106, v50
	v_sub_f32_e32 v76, v104, v50
	v_exp_f32_e32 v77, v77
	v_exp_f32_e32 v76, v76
	v_mov_b32_e32 v106, v165
	v_cndmask_b32_e32 v77, 0, v77, vcc
	v_cmp_lt_f32_e32 vcc, s97, v104
	s_nop 1
	v_cndmask_b32_e32 v76, 0, v76, vcc
	v_cmp_lt_f32_e32 vcc, s97, v91
	s_nop 1
	v_cndmask_b32_e32 v79, 0, v79, vcc
	v_cmp_lt_f32_e32 vcc, s97, v101
	v_ashrrev_i32_e32 v101, 6, v158
	s_nop 0
	v_cndmask_b32_e32 v78, 0, v78, vcc
	v_pk_add_f32 v[80:81], v[76:77], v[78:79]
	v_cmp_lt_f32_e32 vcc, s97, v90
	v_add_f32_e32 v52, v80, v52
	v_add_f32_e32 v52, v81, v52
	v_sub_f32_e32 v81, v90, v50
	v_sub_f32_e32 v80, v88, v50
	v_exp_f32_e32 v81, v81
	v_exp_f32_e32 v80, v80
	v_sub_f32_e32 v90, v85, v50
	v_exp_f32_e32 v90, v90
	v_cndmask_b32_e32 v81, 0, v81, vcc
	v_cmp_lt_f32_e32 vcc, s97, v88
	s_nop 1
	v_cndmask_b32_e32 v80, 0, v80, vcc
	v_cmp_lt_f32_e32 vcc, s97, v85
	v_sub_f32_e32 v85, v89, v50
	v_exp_f32_e32 v85, v85
	v_cndmask_b32_e32 v91, 0, v90, vcc
	v_cmp_lt_f32_e32 vcc, s97, v86
	v_sub_f32_e32 v86, v84, v50
	v_exp_f32_e32 v86, v86
	v_cndmask_b32_e32 v90, 0, v82, vcc
	v_sub_f32_e32 v82, v87, v50
	v_exp_f32_e32 v82, v82
	v_sub_f32_e32 v50, v83, v50
	v_exp_f32_e32 v50, v50
	v_cmp_lt_f32_e32 vcc, s97, v89
	v_pk_add_f32 v[102:103], v[80:81], v[90:91]
	s_nop 0
	v_cndmask_b32_e32 v89, 0, v85, vcc
	v_cmp_lt_f32_e32 vcc, s97, v87
	v_add_f32_e32 v52, v102, v52
	v_add_f32_e32 v52, v103, v52
	v_cndmask_b32_e32 v88, 0, v82, vcc
	v_cmp_lt_f32_e32 vcc, s97, v83
	v_add_u32_e32 v102, -1, v101
	s_nop 0
	v_cndmask_b32_e32 v83, 0, v50, vcc
	v_cmp_lt_f32_e32 vcc, s97, v84
	s_nop 1
	v_cndmask_b32_e32 v82, 0, v86, vcc
	v_pk_add_f32 v[84:85], v[88:89], v[82:83]
	s_nop 0
	v_add_f32_e32 v50, v84, v52
	v_add_f32_e32 v50, v85, v50
	v_mov_b32_e32 v52, v50
	s_nop 1
	v_permlane16_swap_b32_e32 v50, v52
	v_add_f32_e32 v50, v50, v52
	v_mov_b32_e32 v52, v50
	s_nop 1
	v_permlane32_swap_b32_e32 v50, v52
	v_pk_add_f32 v[50:51], v[50:51], v[52:53]
	s_nop 0
	v_div_scale_f32 v52, s[0:1], v51, v51, 1.0
	v_rcp_f32_e32 v53, v52
	s_nop 0
	v_fma_f32 v84, -v52, v53, 1.0
	v_fmac_f32_e32 v53, v84, v53
	v_div_scale_f32 v84, vcc, 1.0, v51, 1.0
	v_mul_f32_e32 v85, v84, v53
	v_fma_f32 v86, -v52, v85, v84
	v_fmac_f32_e32 v85, v86, v53
	v_fma_f32 v52, -v52, v85, v84
	v_div_fmas_f32 v52, v52, v53, v85
	v_div_fixup_f32 v52, v52, v51, 1.0
	v_cmp_lt_f32_e32 vcc, 0, v51
	s_nop 1
	v_cndmask_b32_e32 v112, 0, v52, vcc
	v_pk_mul_f32 v[118:119], v[112:113], v[30:31] op_sel_hi:[0,1]
	v_div_scale_f32 v30, s[0:1], v50, v50, 1.0
	v_rcp_f32_e32 v31, v30
	v_pk_mul_f32 v[114:115], v[112:113], v[18:19] op_sel_hi:[0,1]
	v_pk_mul_f32 v[26:27], v[112:113], v[26:27] op_sel_hi:[0,1]
	v_pk_mul_f32 v[116:117], v[112:113], v[20:21] op_sel_hi:[0,1]
	v_fma_f32 v51, -v30, v31, 1.0
	v_fmac_f32_e32 v31, v51, v31
	v_div_scale_f32 v51, vcc, 1.0, v50, 1.0
	v_mul_f32_e32 v52, v51, v31
	v_fma_f32 v53, -v30, v52, v51
	v_fmac_f32_e32 v52, v53, v31
	v_fma_f32 v30, -v30, v52, v51
	v_div_fmas_f32 v30, v30, v31, v52
	v_div_fixup_f32 v30, v30, v50, 1.0
	v_cmp_lt_f32_e32 vcc, 0, v50
	v_pk_mul_f32 v[120:121], v[112:113], v[22:23] op_sel_hi:[0,1]
	v_pk_mul_f32 v[122:123], v[112:113], v[28:29] op_sel_hi:[0,1]
	v_cndmask_b32_e32 v30, 0, v30, vcc
	v_pk_mul_f32 v[124:125], v[112:113], v[24:25] op_sel_hi:[0,1]
	v_pk_mul_f32 v[126:127], v[112:113], v[34:35] op_sel_hi:[0,1]
	v_pk_mul_f32 v[128:129], v[112:113], v[32:33] op_sel_hi:[0,1]
	v_pk_mul_f32 v[130:131], v[112:113], v[38:39] op_sel_hi:[0,1]
	v_pk_mul_f32 v[132:133], v[112:113], v[36:37] op_sel_hi:[0,1]
	v_pk_mul_f32 v[134:135], v[112:113], v[42:43] op_sel_hi:[0,1]
	v_pk_mul_f32 v[136:137], v[112:113], v[40:41] op_sel_hi:[0,1]
	v_pk_mul_f32 v[138:139], v[112:113], v[92:93] op_sel_hi:[0,1]
	v_pk_mul_f32 v[140:141], v[112:113], v[44:45] op_sel_hi:[0,1]
	v_pk_mul_f32 v[142:143], v[112:113], v[94:95] op_sel_hi:[0,1]
	v_pk_mul_f32 v[144:145], v[30:31], v[54:55] op_sel_hi:[0,1]
	v_pk_mul_f32 v[152:153], v[30:31], v[46:47] op_sel_hi:[0,1]
	v_pk_mul_f32 v[154:155], v[30:31], v[56:57] op_sel_hi:[0,1]
	v_pk_mul_f32 v[162:163], v[30:31], v[48:49] op_sel_hi:[0,1]
	v_pk_mul_f32 v[170:171], v[30:31], v[68:69] op_sel_hi:[0,1]
	v_pk_mul_f32 v[176:177], v[30:31], v[58:59] op_sel_hi:[0,1]
	v_pk_mul_f32 v[178:179], v[30:31], v[70:71] op_sel_hi:[0,1]
	v_pk_mul_f32 v[180:181], v[30:31], v[60:61] op_sel_hi:[0,1]
	v_pk_mul_f32 v[182:183], v[30:31], v[72:73] op_sel_hi:[0,1]
	v_pk_mul_f32 v[184:185], v[30:31], v[76:77] op_sel_hi:[0,1]
	v_pk_mul_f32 v[186:187], v[30:31], v[74:75] op_sel_hi:[0,1]
	v_pk_mul_f32 v[188:189], v[30:31], v[78:79] op_sel_hi:[0,1]
	v_pk_mul_f32 v[190:191], v[30:31], v[80:81] op_sel_hi:[0,1]
	v_pk_mul_f32 v[192:193], v[30:31], v[88:89] op_sel_hi:[0,1]
	v_pk_mul_f32 v[194:195], v[30:31], v[90:91] op_sel_hi:[0,1]
	v_pk_mul_f32 v[196:197], v[30:31], v[82:83] op_sel_hi:[0,1]
	v_add_f32_e32 v107, v26, v152
	v_add_f32_e32 v109, v118, v162
	v_add_f32_e32 v103, v27, v153
	v_add_f32_e32 v104, v119, v163
	v_pk_fma_f32 v[86:87], v[112:113], v[18:19], v[144:145] op_sel_hi:[0,1,1]
	v_pk_fma_f32 v[84:85], v[112:113], v[20:21], v[154:155] op_sel_hi:[0,1,1]
	v_pk_fma_f32 v[68:69], v[112:113], v[28:29], v[176:177] op_sel_hi:[0,1,1]
	v_pk_fma_f32 v[76:77], v[112:113], v[22:23], v[170:171] op_sel_hi:[0,1,1]
	v_pk_fma_f32 v[70:71], v[112:113], v[34:35], v[180:181] op_sel_hi:[0,1,1]
	v_pk_fma_f32 v[80:81], v[112:113], v[24:25], v[178:179] op_sel_hi:[0,1,1]
	v_pk_fma_f32 v[46:47], v[112:113], v[38:39], v[184:185] op_sel_hi:[0,1,1]
	v_pk_fma_f32 v[54:55], v[112:113], v[32:33], v[182:183] op_sel_hi:[0,1,1]
	v_pk_fma_f32 v[48:49], v[112:113], v[42:43], v[188:189] op_sel_hi:[0,1,1]
	v_pk_fma_f32 v[58:59], v[112:113], v[36:37], v[186:187] op_sel_hi:[0,1,1]
	v_pk_fma_f32 v[30:31], v[112:113], v[92:93], v[192:193] op_sel_hi:[0,1,1]
	v_pk_fma_f32 v[38:39], v[112:113], v[40:41], v[190:191] op_sel_hi:[0,1,1]
	v_pk_fma_f32 v[32:33], v[112:113], v[94:95], v[196:197] op_sel_hi:[0,1,1]
	v_pk_fma_f32 v[42:43], v[112:113], v[44:45], v[194:195] op_sel_hi:[0,1,1]
	v_pk_mul_f32 v[20:21], v[66:67], v[114:115] op_sel_hi:[0,1]
	v_pk_mul_f32 v[18:19], v[66:67], v[26:27] op_sel_hi:[0,1]
	v_pk_mul_f32 v[28:29], v[66:67], v[116:117] op_sel_hi:[0,1]
	v_pk_mul_f32 v[26:27], v[66:67], v[118:119] op_sel_hi:[0,1]
	v_pk_mul_f32 v[22:23], v[66:67], v[122:123] op_sel_hi:[0,1]
	v_pk_mul_f32 v[24:25], v[66:67], v[120:121] op_sel_hi:[0,1]
	v_pk_mul_f32 v[92:93], v[66:67], v[126:127] op_sel_hi:[0,1]
	v_pk_mul_f32 v[94:95], v[66:67], v[124:125] op_sel_hi:[0,1]
	v_pk_mul_f32 v[112:113], v[66:67], v[130:131] op_sel_hi:[0,1]
	v_pk_mul_f32 v[114:115], v[66:67], v[128:129] op_sel_hi:[0,1]
	v_pk_mul_f32 v[116:117], v[66:67], v[134:135] op_sel_hi:[0,1]
	v_pk_mul_f32 v[118:119], v[66:67], v[132:133] op_sel_hi:[0,1]
	v_pk_mul_f32 v[120:121], v[66:67], v[138:139] op_sel_hi:[0,1]
	v_pk_mul_f32 v[122:123], v[66:67], v[136:137] op_sel_hi:[0,1]
	v_pk_mul_f32 v[124:125], v[66:67], v[142:143] op_sel_hi:[0,1]
	v_pk_mul_f32 v[126:127], v[66:67], v[140:141] op_sel_hi:[0,1]
	v_cvt_pk_bf16_f32 v18, v18, v19
	v_cvt_pk_bf16_f32 v19, v20, v21
	v_cvt_pk_bf16_f32 v20, v24, v25
	v_cvt_pk_bf16_f32 v21, v22, v23
	v_cvt_pk_bf16_f32 v22, v114, v115
	v_cvt_pk_bf16_f32 v23, v112, v113
	v_cvt_pk_bf16_f32 v24, v122, v123
	v_cvt_pk_bf16_f32 v25, v120, v121
	v_cvt_pk_bf16_f32 v26, v26, v27
	v_cvt_pk_bf16_f32 v27, v28, v29
	v_cvt_pk_bf16_f32 v28, v94, v95
	v_cvt_pk_bf16_f32 v29, v92, v93
	v_cvt_pk_bf16_f32 v92, v118, v119
	v_cvt_pk_bf16_f32 v93, v116, v117
	v_cvt_pk_bf16_f32 v94, v126, v127
	v_cvt_pk_bf16_f32 v95, v124, v125
	v_pk_mul_f32 v[114:115], v[64:65], v[144:145] op_sel_hi:[0,1]
	v_pk_mul_f32 v[112:113], v[64:65], v[152:153] op_sel_hi:[0,1]
	v_pk_mul_f32 v[122:123], v[64:65], v[154:155] op_sel_hi:[0,1]
	v_pk_mul_f32 v[120:121], v[64:65], v[162:163] op_sel_hi:[0,1]
	v_pk_mul_f32 v[116:117], v[64:65], v[176:177] op_sel_hi:[0,1]
	v_pk_mul_f32 v[118:119], v[64:65], v[170:171] op_sel_hi:[0,1]
	v_pk_mul_f32 v[124:125], v[64:65], v[180:181] op_sel_hi:[0,1]
	v_pk_mul_f32 v[126:127], v[64:65], v[178:179] op_sel_hi:[0,1]
	v_pk_mul_f32 v[128:129], v[64:65], v[184:185] op_sel_hi:[0,1]
	v_pk_mul_f32 v[130:131], v[64:65], v[182:183] op_sel_hi:[0,1]
	v_pk_mul_f32 v[132:133], v[64:65], v[188:189] op_sel_hi:[0,1]
	v_pk_mul_f32 v[134:135], v[64:65], v[186:187] op_sel_hi:[0,1]
	v_pk_mul_f32 v[136:137], v[64:65], v[192:193] op_sel_hi:[0,1]
	v_pk_mul_f32 v[138:139], v[64:65], v[190:191] op_sel_hi:[0,1]
	v_pk_mul_f32 v[140:141], v[64:65], v[196:197] op_sel_hi:[0,1]
	v_pk_mul_f32 v[142:143], v[64:65], v[194:195] op_sel_hi:[0,1]
	v_bfe_u32 v64, v1, 2, 2
	v_or_b32_e32 v64, v160, v64
	v_mul_u32_u24_e32 v163, 0xa0, v64
	v_add3_u32 v64, 0, v163, v166
	v_cvt_pk_bf16_f32 v112, v112, v113
	v_cvt_pk_bf16_f32 v113, v114, v115
	v_cvt_pk_bf16_f32 v115, v116, v117
	v_cvt_pk_bf16_f32 v117, v128, v129
	v_add_u32_e32 v168, 0x2800, v64
	ds_read_b64_tr_b16 v[128:129], v168 offset:0
	v_cvt_pk_bf16_f32 v116, v130, v131
	ds_read_b64_tr_b16 v[130:131], v168 offset:2560
	v_cvt_pk_bf16_f32 v120, v120, v121
	v_cvt_pk_bf16_f32 v121, v122, v123
	v_cvt_pk_bf16_f32 v123, v124, v125
	v_cvt_pk_bf16_f32 v125, v132, v133
	ds_read_b64_tr_b16 v[132:133], v168 offset:32
	v_cvt_pk_bf16_f32 v124, v134, v135
	ds_read_b64_tr_b16 v[134:135], v168 offset:2592
	v_cvt_pk_bf16_f32 v114, v118, v119
	v_cvt_pk_bf16_f32 v119, v136, v137
	ds_read_b64_tr_b16 v[136:137], v168 offset:64
	v_cvt_pk_bf16_f32 v118, v138, v139
	ds_read_b64_tr_b16 v[138:139], v168 offset:2624
	v_cvt_pk_bf16_f32 v122, v126, v127
	v_cvt_pk_bf16_f32 v127, v140, v141
	ds_read_b64_tr_b16 v[140:141], v168 offset:96
	v_cvt_pk_bf16_f32 v126, v142, v143
	ds_read_b64_tr_b16 v[142:143], v168 offset:2656
	ds_read_b64_tr_b16 v[152:153], v168 offset:5120
	ds_read_b64_tr_b16 v[154:155], v168 offset:7680
	ds_read_b64_tr_b16 v[176:177], v168 offset:5152
	ds_read_b64_tr_b16 v[178:179], v168 offset:7712
	ds_read_b64_tr_b16 v[180:181], v168 offset:5184
	ds_read_b64_tr_b16 v[182:183], v168 offset:7744
	ds_read_b64_tr_b16 v[184:185], v168 offset:5216
	ds_read_b64_tr_b16 v[186:187], v168 offset:7776
	s_waitcnt lgkmcnt(8)
	v_mov_b32_e32 v90, v165
	v_mov_b32_e32 v88, v165
	v_mov_b32_e32 v91, v165
	v_mov_b32_e32 v89, v165
	v_mov_b32_e32 v78, v165
	v_mov_b32_e32 v82, v165
	v_mov_b32_e32 v79, v165
	v_mov_b32_e32 v83, v165
	v_mov_b32_e32 v74, v165
	v_mov_b32_e32 v72, v165
	v_mov_b32_e32 v75, v165
	v_mov_b32_e32 v73, v165
	v_mov_b32_e32 v56, v165
	v_mov_b32_e32 v60, v165
	v_mov_b32_e32 v57, v165
	v_mov_b32_e32 v61, v165
	v_mov_b32_e32 v52, v165
	v_mov_b32_e32 v50, v165
	v_mov_b32_e32 v53, v165
	v_mov_b32_e32 v51, v165
	v_mov_b32_e32 v40, v165
	v_mov_b32_e32 v44, v165
	v_mov_b32_e32 v41, v165
	v_mov_b32_e32 v45, v165
	v_mov_b32_e32 v36, v165
	v_mov_b32_e32 v34, v165
	v_mov_b32_e32 v37, v165
	v_mov_b32_e32 v35, v165
	v_mov_b32_dpp v110, v107 row_ror:8 row_mask:0xf bank_mask:0xf
	v_mov_b32_dpp v111, v109 row_ror:8 row_mask:0xf bank_mask:0xf
	v_mov_b32_dpp v105, v103 row_ror:8 row_mask:0xf bank_mask:0xf
	v_mov_b32_dpp v106, v104 row_ror:8 row_mask:0xf bank_mask:0xf
	v_mov_b32_dpp v90, v86 row_ror:8 row_mask:0xf bank_mask:0xf
	v_mov_b32_dpp v88, v84 row_ror:8 row_mask:0xf bank_mask:0xf
	v_mov_b32_dpp v91, v87 row_ror:8 row_mask:0xf bank_mask:0xf
	v_mov_b32_dpp v89, v85 row_ror:8 row_mask:0xf bank_mask:0xf
	v_mov_b32_dpp v78, v76 row_ror:8 row_mask:0xf bank_mask:0xf
	v_mov_b32_dpp v82, v80 row_ror:8 row_mask:0xf bank_mask:0xf
	v_mov_b32_dpp v79, v77 row_ror:8 row_mask:0xf bank_mask:0xf
	v_mov_b32_dpp v83, v81 row_ror:8 row_mask:0xf bank_mask:0xf
	v_mov_b32_dpp v74, v68 row_ror:8 row_mask:0xf bank_mask:0xf
	v_mov_b32_dpp v72, v70 row_ror:8 row_mask:0xf bank_mask:0xf
	v_mov_b32_dpp v75, v69 row_ror:8 row_mask:0xf bank_mask:0xf
	v_mov_b32_dpp v73, v71 row_ror:8 row_mask:0xf bank_mask:0xf
	v_mov_b32_dpp v56, v54 row_ror:8 row_mask:0xf bank_mask:0xf
	v_mov_b32_dpp v60, v58 row_ror:8 row_mask:0xf bank_mask:0xf
	v_mov_b32_dpp v57, v55 row_ror:8 row_mask:0xf bank_mask:0xf
	v_mov_b32_dpp v61, v59 row_ror:8 row_mask:0xf bank_mask:0xf
	v_mov_b32_dpp v52, v46 row_ror:8 row_mask:0xf bank_mask:0xf
	v_mov_b32_dpp v50, v48 row_ror:8 row_mask:0xf bank_mask:0xf
	v_mov_b32_dpp v53, v47 row_ror:8 row_mask:0xf bank_mask:0xf
	v_mov_b32_dpp v51, v49 row_ror:8 row_mask:0xf bank_mask:0xf
	v_mov_b32_dpp v40, v38 row_ror:8 row_mask:0xf bank_mask:0xf
	v_mov_b32_dpp v44, v42 row_ror:8 row_mask:0xf bank_mask:0xf
	v_mov_b32_dpp v41, v39 row_ror:8 row_mask:0xf bank_mask:0xf
	v_mov_b32_dpp v45, v43 row_ror:8 row_mask:0xf bank_mask:0xf
	v_mov_b32_dpp v36, v30 row_ror:8 row_mask:0xf bank_mask:0xf
	v_mov_b32_dpp v34, v32 row_ror:8 row_mask:0xf bank_mask:0xf
	v_mov_b32_dpp v37, v31 row_ror:8 row_mask:0xf bank_mask:0xf
	v_mov_b32_dpp v35, v33 row_ror:8 row_mask:0xf bank_mask:0xf
	s_setprio 1
	v_mfma_f32_16x16x32_bf16 v[188:191], v[128:131], v[18:21], 0
	s_waitcnt lgkmcnt(0)
	v_mfma_f32_16x16x32_bf16 v[192:195], v[132:135], v[18:21], 0
	v_mfma_f32_16x16x32_bf16 v[196:199], v[136:139], v[18:21], 0
	v_mfma_f32_16x16x32_bf16 v[18:21], v[140:143], v[18:21], 0
	v_mfma_f32_16x16x32_bf16 v[128:131], v[128:131], v[112:115], 0
	v_mfma_f32_16x16x32_bf16 v[132:135], v[132:135], v[112:115], 0
	v_mfma_f32_16x16x32_bf16 v[136:139], v[136:139], v[112:115], 0
	v_mfma_f32_16x16x32_bf16 v[112:115], v[140:143], v[112:115], 0
	v_mfma_f32_16x16x32_bf16 v[140:143], v[152:155], v[22:25], v[188:191]
	v_mfma_f32_16x16x32_bf16 v[128:131], v[152:155], v[116:119], v[128:131]
	v_mfma_f32_16x16x32_bf16 v[152:155], v[176:179], v[22:25], v[192:195]
	v_mfma_f32_16x16x32_bf16 v[132:135], v[176:179], v[116:119], v[132:135]
	v_mfma_f32_16x16x32_bf16 v[176:179], v[180:183], v[22:25], v[196:199]
	v_mfma_f32_16x16x32_bf16 v[18:21], v[184:187], v[22:25], v[18:21]
	v_mfma_f32_16x16x32_bf16 v[22:25], v[184:187], v[116:119], v[112:115]
	v_mfma_f32_16x16x32_bf16 v[136:139], v[180:183], v[116:119], v[136:139]
	s_setprio 0
	v_add_u32_e32 v170, 0x7800, v64
	ds_read_b64_tr_b16 v[112:113], v170 offset:0
	ds_read_b64_tr_b16 v[114:115], v170 offset:2560
	ds_read_b64_tr_b16 v[116:117], v170 offset:32
	ds_read_b64_tr_b16 v[118:119], v170 offset:2592
	ds_read_b64_tr_b16 v[180:181], v170 offset:64
	ds_read_b64_tr_b16 v[182:183], v170 offset:2624
	ds_read_b64_tr_b16 v[184:185], v170 offset:96
	ds_read_b64_tr_b16 v[186:187], v170 offset:2656
	ds_read_b64_tr_b16 v[188:189], v170 offset:5120
	ds_read_b64_tr_b16 v[190:191], v170 offset:7680
	ds_read_b64_tr_b16 v[192:193], v170 offset:5152
	ds_read_b64_tr_b16 v[194:195], v170 offset:7712
	ds_read_b64_tr_b16 v[196:197], v170 offset:5184
	ds_read_b64_tr_b16 v[198:199], v170 offset:7744
	ds_read_b64_tr_b16 v[200:201], v170 offset:5216
	ds_read_b64_tr_b16 v[202:203], v170 offset:7776
	s_waitcnt lgkmcnt(8)
	s_setprio 1
	v_mfma_f32_16x16x32_bf16 v[18:21], v[184:187], v[26:29], v[18:21]
	s_waitcnt lgkmcnt(0)
	v_mfma_f32_16x16x32_bf16 v[22:25], v[184:187], v[120:123], v[22:25]
	v_mfma_f32_16x16x32_bf16 v[140:143], v[112:115], v[26:29], v[140:143]
	v_mfma_f32_16x16x32_bf16 v[112:115], v[112:115], v[120:123], v[128:131]
	v_mfma_f32_16x16x32_bf16 v[128:131], v[116:119], v[26:29], v[152:155]
	v_mfma_f32_16x16x32_bf16 v[116:119], v[116:119], v[120:123], v[132:135]
	v_mfma_f32_16x16x32_bf16 v[132:135], v[180:183], v[26:29], v[176:179]
	v_mfma_f32_16x16x32_bf16 v[136:139], v[180:183], v[120:123], v[136:139]
	v_mfma_f32_16x16x32_bf16 v[26:29], v[188:191], v[92:95], v[140:143]
	v_mfma_f32_16x16x32_bf16 v[18:21], v[200:203], v[92:95], v[18:21]
	v_mfma_f32_16x16x32_bf16 v[22:25], v[200:203], v[124:127], v[22:25]
	v_mfma_f32_16x16x32_bf16 v[112:115], v[188:191], v[124:127], v[112:115]
	v_mfma_f32_16x16x32_bf16 v[120:123], v[192:195], v[92:95], v[128:131]
	v_mfma_f32_16x16x32_bf16 v[116:119], v[192:195], v[124:127], v[116:119]
	v_mfma_f32_16x16x32_bf16 v[128:131], v[196:199], v[92:95], v[132:135]
	v_mfma_f32_16x16x32_bf16 v[132:135], v[196:199], v[124:127], v[136:139]
	s_setprio 0
	v_mul_u32_u24_e32 v64, 0x210, v108
	v_and_b32_e32 v66, 0x80, v151
	v_add3_u32 v64, s26, v64, v99
	v_add_u32_e32 v64, v64, v66
	v_cvt_pk_bf16_f32 v26, v26, v27
	v_cvt_pk_bf16_f32 v27, v28, v29
	v_cvt_pk_bf16_f32 v28, v120, v121
	v_cvt_pk_bf16_f32 v29, v122, v123
	v_add_u32_e32 v161, 0xa000, v64
	ds_write2_b64 v161, v[26:27], v[28:29] offset1:4
	v_cvt_pk_bf16_f32 v26, v128, v129
	v_cvt_pk_bf16_f32 v27, v130, v131
	v_cvt_pk_bf16_f32 v18, v18, v19
	v_cvt_pk_bf16_f32 v19, v20, v21
	ds_write2_b64 v161, v[26:27], v[18:19] offset0:8 offset1:12
	v_cvt_pk_bf16_f32 v18, v112, v113
	v_cvt_pk_bf16_f32 v19, v114, v115
	v_cvt_pk_bf16_f32 v20, v116, v117
	v_cvt_pk_bf16_f32 v21, v118, v119
	v_readlane_b32 s24, v240, 8
	ds_write2_b64 v161, v[18:19], v[20:21] offset0:32 offset1:36
	v_cvt_pk_bf16_f32 v18, v132, v133
	v_cvt_pk_bf16_f32 v19, v134, v135
	v_cvt_pk_bf16_f32 v20, v22, v23
	v_cvt_pk_bf16_f32 v21, v24, v25
	s_ashr_i32 s7, s6, 31
	v_lshl_add_u64 v[152:153], s[78:79], 0, v[62:63]
	v_readlane_b32 s25, v240, 9
	ds_write2_b64 v161, v[18:19], v[20:21] offset0:40 offset1:44
	v_lshl_add_u64 v[18:19], v[152:153], 0, s[6:7]
	v_mov_b64_e32 v[20:21], s[24:25]
	v_mad_u64_u32 v[20:21], s[0:1], v18, s33, v[20:21]
	v_mad_i32_i24 v21, v19, s33, v21
	s_lshl_b32 s21, s76, 7
	s_lshl_b32 s76, s76, 8
	v_lshl_add_u64 v[18:19], v[20:21], 0, s[76:77]
	v_lshlrev_b32_e32 v164, 1, v100
	v_lshl_add_u64 v[22:23], v[18:19], 0, v[164:165]
	global_load_dwordx4 v[18:21], v[22:23], off offset:1024
	s_nop 0
	global_load_dwordx4 v[22:25], v[22:23], off offset:1152
	v_lshlrev_b32_e64 v29, v101, 1
	s_movk_i32 s0, 0x800
	v_ashrrev_i32_e32 v62, 11, v158
	v_cmp_gt_u32_e32 vcc, s0, v158
	v_or_b32_e32 v26, 1, v29
	s_nop 0
	v_cndmask_b32_e32 v26, 1, v26, vcc
	v_cmp_eq_u32_e32 vcc, 1, v62
	s_nop 1
	v_cndmask_b32_e32 v27, 0, v29, vcc
	v_cmp_eq_u32_e32 vcc, 2, v62
	s_nop 1
	v_cndmask_b32_e32 v28, 0, v29, vcc
	v_cmp_eq_u32_e32 vcc, 3, v62
	s_nop 1
	v_cndmask_b32_e32 v29, 0, v29, vcc
	v_cmp_lt_i32_e32 vcc, 0, v101
	s_and_saveexec_b64 s[0:1], vcc
	s_cbranch_execz .LBB0_1402
	v_lshlrev_b32_e64 v62, v102, 1
	v_lshrrev_b32_e32 v63, 5, v102
	v_cmp_gt_u32_e32 vcc, 33, v101
	s_nop 1
	v_cndmask_b32_e32 v64, 0, v62, vcc
	v_cmp_eq_u32_e32 vcc, 1, v63
	v_or_b32_e32 v26, v26, v64
	s_nop 0
	v_cndmask_b32_e32 v64, 0, v62, vcc
	v_cmp_eq_u32_e32 vcc, 2, v63
	v_or_b32_e32 v27, v64, v27
	s_nop 0
	v_cndmask_b32_e32 v64, 0, v62, vcc
	v_cmp_eq_u32_e32 vcc, 3, v63
	v_or_b32_e32 v28, v64, v28
	s_nop 0
	v_cndmask_b32_e32 v62, 0, v62, vcc
	v_or_b32_e32 v29, v62, v29
